# prompt-attention unit prologue: second key tile's loads requested together with the first tile and Q (de-serialised prologue)
# speedup vs baseline: 1.0092x; 1.0092x over previous
.LBB0_465:
	s_lshl_b32 s4, s90, 6
	s_and_b32 s6, s4, 0x3800
	s_lshl_b32 s4, s90, 7
	s_and_b32 s24, s4, 0x380
	s_xor_b32 s4, s24, 0x780
	s_cmpk_lt_u32 s90, 0x100
	s_cselect_b32 s14, s4, s24
	s_or_b32 s91, s14, s6
	s_lshl_b32 s4, s91, 10
	s_add_u32 s4, s13, s4
	s_addc_u32 s5, s35, 0
	s_lshl_b32 s25, s15, 8
	s_add_u32 s4, s4, s25
	s_addc_u32 s5, s5, 0
	s_lshl_b32 s26, s6, 10
	s_add_u32 s6, s70, s26
	s_addc_u32 s7, s71, 0
	s_add_u32 s6, s6, s25
	s_addc_u32 s7, s7, 0
	s_add_u32 s26, s82, s26
	s_addc_u32 s27, s83, 0
	s_add_u32 s68, s26, s25
	s_addc_u32 s69, s27, 0
	s_add_i32 s25, s14, 0x80
	s_lshr_b32 s27, s25, 6
	s_add_i32 s26, s27, -1
	s_cmpk_gt_u32 s90, 0xff
	s_cselect_b64 s[64:65], -1, 0
	s_and_b64 s[28:29], s[64:65], exec
	v_mbcnt_lo_u32_b32 v0, -1, 0
	v_mbcnt_hi_u32_b32 v0, -1, v0
	s_cselect_b32 s29, s26, 0
	v_add_u32_e32 v148, s73, v0
	s_lshl_b32 s25, s29, 6
	v_ashrrev_i32_e32 v158, 4, v148
	v_add_u32_e32 v0, s25, v158
	v_ashrrev_i32_e32 v1, 31, v0
	v_lshlrev_b64 v[8:9], 10, v[0:1]
	v_add_u32_e32 v0, 32, v0
	v_and_b32_e32 v32, 15, v148
	v_ashrrev_i32_e32 v1, 31, v0
	v_lshlrev_b32_e32 v4, 4, v32
	v_lshlrev_b64 v[10:11], 10, v[0:1]
	v_or_b32_e32 v8, v8, v4
	v_or_b32_e32 v10, v10, v4
	v_lshl_add_u64 v[2:3], s[68:69], 0, v[8:9]
	v_lshl_add_u64 v[4:5], s[68:69], 0, v[10:11]
	v_lshl_add_u64 v[8:9], s[6:7], 0, v[8:9]
	v_lshl_add_u64 v[12:13], s[6:7], 0, v[10:11]
	global_load_dwordx4 v[0:3], v[2:3], off
	s_nop 0
	global_load_dwordx4 v[4:7], v[4:5], off
	s_nop 0
	global_load_dwordx4 v[8:11], v[8:9], off
	s_nop 0
	global_load_dwordx4 v[12:15], v[12:13], off
	v_and_b32_e32 v151, 31, v148
	v_bfe_u32 v150, v148, 6, 2
	v_ashrrev_i32_e32 v149, 8, v148
	v_lshl_or_b32 v153, v150, 5, v151
	v_lshlrev_b32_e32 v16, 10, v153
	v_mov_b32_e32 v17, v128
	v_lshlrev_b32_e32 v18, 6, v149
	v_bfe_u32 v33, v148, 5, 1
	v_lshl_add_u64 v[16:17], s[4:5], 0, v[16:17]
	v_ashrrev_i32_e32 v19, 31, v18
	v_lshl_add_u64 v[16:17], v[18:19], 1, v[16:17]
	v_lshlrev_b32_e32 v18, 4, v33
	v_mov_b32_e32 v19, v128
	v_lshl_add_u64 v[16:17], v[16:17], 0, v[18:19]
	global_load_dwordx4 v[112:115], v[16:17], off nt
	global_load_dwordx4 v[116:119], v[16:17], off offset:32 nt
	global_load_dwordx4 v[124:127], v[16:17], off offset:64 nt
	global_load_dwordx4 v[120:123], v[16:17], off offset:96 nt
	s_and_b64 s[30:31], s[64:65], exec
	s_cselect_b32 s5, s24, 64
	v_add_u32_e32 v230, s5, v158
	v_ashrrev_i32_e32 v231, 31, v230
	v_lshlrev_b64 v[232:233], 10, v[230:231]
	v_lshlrev_b32_e32 v234, 4, v32
	v_add_u32_e32 v230, 32, v230
	v_ashrrev_i32_e32 v231, 31, v230
	v_lshlrev_b64 v[230:231], 10, v[230:231]
	v_or_b32_e32 v232, v232, v234
	v_or_b32_e32 v230, v230, v234
	v_lshl_add_u64 v[236:237], s[68:69], 0, v[232:233]
	v_lshl_add_u64 v[240:241], s[68:69], 0, v[230:231]
	v_lshl_add_u64 v[244:245], s[6:7], 0, v[232:233]
	v_lshl_add_u64 v[226:227], s[6:7], 0, v[230:231]
	global_load_dwordx4 v[236:239], v[236:237], off
	global_load_dwordx4 v[240:243], v[240:241], off
	global_load_dwordx4 v[244:247], v[244:245], off
	global_load_dwordx4 v[226:229], v[226:227], off
	v_and_b32_e32 v20, 0xfffff0, v158
	v_lshlrev_b32_e32 v21, 1, v158
	v_lshrrev_b32_e32 v22, 1, v158
	v_and_b32_e32 v23, 3, v158
	v_add_u32_e32 v170, 32, v158
	v_and_or_b32 v20, v21, 8, v20
	v_and_or_b32 v21, v22, 4, v23
	v_and_b32_e32 v22, 0xfffff0, v170
	v_lshlrev_b32_e32 v23, 1, v170
	v_bfe_u32 v18, v148, 2, 2
	v_lshrrev_b32_e32 v20, 1, v20
	v_and_or_b32 v22, v23, 8, v22
	v_lshlrev_b32_e32 v19, 4, v148
	v_or_b32_e32 v20, v20, v18
	v_lshrrev_b32_e32 v22, 1, v22
	v_and_b32_e32 v19, 48, v19
	v_lshlrev_b32_e32 v21, 6, v21
	v_lshlrev_b32_e32 v20, 9, v20
	v_or_b32_e32 v18, v22, v18
	v_lshlrev_b32_e32 v24, 10, v32
	v_bitop3_b32 v25, v148, v158, 7 bitop3:0x6c
	v_bitop3_b32 v26, v170, v148, 7 bitop3:0x78
	v_or3_b32 v20, v20, v21, v19
	v_lshlrev_b32_e32 v18, 9, v18
	v_lshl_add_u32 v25, v25, 4, v24
	v_lshl_add_u32 v23, v26, 4, v24
	v_or3_b32 v18, v18, v21, v19
	v_add_u32_e32 v174, 0, v20
	v_lshl_or_b32 v42, v149, 3, v33
	v_add_u32_e32 v171, 0, v25
	v_add_u32_e32 v172, 0, v23
	v_add_u32_e32 v175, 0, v18
	s_waitcnt vmcnt(4)
	v_lshlrev_b32_e32 v155, 2, v33
	v_or_b32_e32 v159, s14, v153
	v_or_b32_e32 v16, s25, v155
	v_sub_u32_e32 v16, v16, v159
	v_cvt_f32_i32_e32 v16, v16
	v_mov_b32_e32 v129, v130
	v_or_b32_e32 v43, 32, v151
	s_add_i32 s28, s27, -2
	v_mul_f32_e32 v38, v130, v16
	v_pk_add_f32 v[16:17], v[128:129], v[38:39] op_sel_hi:[1,0]
	v_pk_fma_f32 v[18:19], v[130:131], s[10:11], v[38:39] op_sel_hi:[0,1,0]
	v_pk_fma_f32 v[20:21], v[130:131], s[16:17], v[38:39] op_sel_hi:[0,1,0]
	v_pk_fma_f32 v[22:23], v[130:131], s[18:19], v[38:39] op_sel_hi:[0,1,0]
	s_waitcnt vmcnt(7)
	ds_write_b128 v174, v[0:3]
	s_waitcnt vmcnt(6)
	ds_write_b128 v175, v[4:7]
	s_waitcnt vmcnt(5)
	ds_write_b128 v171, v[8:11] offset:32768
	s_waitcnt vmcnt(4)
	ds_write_b128 v172, v[12:15] offset:32768
	v_lshlrev_b32_e32 v4, 10, v42
	v_bitop3_b32 v0, v33, v148, 31 bitop3:0x78
	v_lshl_or_b32 v0, v0, 4, v4
	v_bitop3_b32 v5, v33, v151, 32 bitop3:0x1e
	v_add_u32_e32 v167, 0, v0
	v_lshl_or_b32 v4, v5, 4, v4
	s_waitcnt lgkmcnt(0)
	s_barrier
	ds_read_b128 v[0:3], v167 offset:32768
	v_add_u32_e32 v162, 0, v4
	ds_read_b128 v[34:37], v162 offset:32768
	v_pk_fma_f32 v[24:25], v[130:131], s[22:23], v[38:39] op_sel_hi:[0,1,0]
	v_pk_fma_f32 v[26:27], v[130:131], s[40:41], v[38:39] op_sel_hi:[0,1,0]
	v_pk_fma_f32 v[28:29], v[130:131], s[42:43], v[38:39] op_sel_hi:[0,1,0]
	v_pk_fma_f32 v[30:31], v[130:131], s[44:45], v[38:39] op_sel_hi:[0,1,0]
	v_pk_fma_f32 v[14:15], v[130:131], s[46:47], v[38:39] op_sel_hi:[0,1,0]
	v_pk_fma_f32 v[12:13], v[130:131], s[48:49], v[38:39] op_sel_hi:[0,1,0]
	s_waitcnt vmcnt(7) lgkmcnt(1)
	v_mfma_f32_32x32x16_bf16 v[16:31], v[0:3], v[112:115], v[16:31]
	v_fma_f32 v10, v130, s50, v38
	v_fma_f32 v11, v130, s51, v38
	v_fma_f32 v8, v130, s52, v38
	v_fma_f32 v9, v130, s53, v38
	v_fma_f32 v6, v130, s54, v38
	v_fma_f32 v7, v130, s55, v38
	v_pk_fma_f32 v[4:5], v[130:131], s[56:57], v[38:39] op_sel_hi:[0,1,0]
	v_pk_fma_f32 v[2:3], v[130:131], s[58:59], v[38:39] op_sel_hi:[0,1,0]
	v_pk_fma_f32 v[0:1], v[130:131], s[60:61], v[38:39] op_sel_hi:[0,1,0]
	v_or_b32_e32 v33, 2, v42
	v_lshlrev_b32_e32 v38, 10, v33
	s_waitcnt lgkmcnt(0)
	v_mfma_f32_32x32x16_bf16 v[0:15], v[34:37], v[112:115], v[0:15]
	v_bitop3_b32 v34, v33, v151, 3 bitop3:0x6c
	v_bitop3_b32 v33, v33, v43, 3 bitop3:0x6c
	v_lshl_or_b32 v34, v34, 4, v38
	v_lshl_or_b32 v33, v33, 4, v38
	v_add_u32_e32 v163, 0, v34
	v_add_u32_e32 v164, 0, v33
	ds_read_b128 v[34:37], v163 offset:32768
	ds_read_b128 v[38:41], v164 offset:32768
	v_or_b32_e32 v33, 4, v42
	s_waitcnt vmcnt(6) lgkmcnt(1)
	v_mfma_f32_32x32x16_bf16 v[16:31], v[34:37], v[116:119], v[16:31]
	v_bitop3_b32 v34, v33, v151, 5 bitop3:0x6c
	s_cmp_lt_u32 s29, s28
	v_subrev_u32_e32 v160, 32, v153
	s_waitcnt lgkmcnt(0)
	v_mfma_f32_32x32x16_bf16 v[0:15], v[38:41], v[116:119], v[0:15]
	v_lshlrev_b32_e32 v38, 10, v33
	v_bitop3_b32 v33, v33, v43, 5 bitop3:0x6c
	v_lshl_or_b32 v34, v34, 4, v38
	v_lshl_or_b32 v33, v33, 4, v38
	v_add_u32_e32 v165, 0, v34
	v_add_u32_e32 v166, 0, v33
	ds_read_b128 v[34:37], v165 offset:32768
	ds_read_b128 v[38:41], v166 offset:32768
	v_or_b32_e32 v33, 6, v42
	s_waitcnt vmcnt(5) lgkmcnt(1)
	v_mfma_f32_32x32x16_bf16 v[16:31], v[34:37], v[124:127], v[16:31]
	v_bitop3_b32 v34, v33, v151, 7 bitop3:0x6c
	s_waitcnt lgkmcnt(0)
	v_mfma_f32_32x32x16_bf16 v[0:15], v[38:41], v[124:127], v[0:15]
	v_lshlrev_b32_e32 v38, 10, v33
	v_bitop3_b32 v33, v33, v43, 7 bitop3:0x6c
	v_lshl_or_b32 v34, v34, 4, v38
	v_lshl_or_b32 v33, v33, 4, v38
	v_add_u32_e32 v168, 0, v34
	v_add_u32_e32 v169, 0, v33
	ds_read_b128 v[34:37], v168 offset:32768
	ds_read_b128 v[38:41], v169 offset:32768
	s_waitcnt vmcnt(4) lgkmcnt(1)
	v_mfma_f32_32x32x16_bf16 v[16:31], v[34:37], v[120:123], v[16:31]
	s_waitcnt lgkmcnt(0)
	v_mfma_f32_32x32x16_bf16 v[0:15], v[38:41], v[120:123], v[0:15]
	s_cbranch_scc1 .LBB0_467
	s_sub_i32 s4, s25, s14
	v_or_b32_e32 v33, s4, v155
	v_cmp_lt_i32_e32 vcc, v33, v153
	v_or_b32_e32 v34, 2, v33
	s_nop 4
	v_cndmask_b32_e32 v17, v145, v17, vcc
	v_cmp_le_i32_e32 vcc, v33, v153
	s_nop 1
	v_cndmask_b32_e32 v16, v145, v16, vcc
	v_cmp_lt_i32_e32 vcc, v33, v160
	s_nop 1
	v_cndmask_b32_e32 v1, v145, v1, vcc
	v_cmp_le_i32_e32 vcc, v33, v160
	s_nop 1
	v_cndmask_b32_e32 v0, v145, v0, vcc
	v_cmp_le_i32_e32 vcc, v34, v153
	s_nop 1
	v_cndmask_b32_e32 v18, v145, v18, vcc
	v_cmp_le_i32_e32 vcc, v34, v160
	v_or_b32_e32 v34, 3, v33
	s_nop 0
	v_cndmask_b32_e32 v2, v145, v2, vcc
	v_cmp_le_i32_e32 vcc, v34, v153
	s_nop 1
	v_cndmask_b32_e32 v19, v145, v19, vcc
	v_cmp_le_i32_e32 vcc, v34, v160
	v_or_b32_e32 v34, 8, v33
	s_nop 0
	v_cndmask_b32_e32 v3, v145, v3, vcc
	v_cmp_le_i32_e32 vcc, v34, v153
	s_nop 1
	v_cndmask_b32_e32 v20, v145, v20, vcc
	v_cmp_le_i32_e32 vcc, v34, v160
	v_or_b32_e32 v34, 9, v33
	s_nop 0
	v_cndmask_b32_e32 v4, v145, v4, vcc
	v_cmp_le_i32_e32 vcc, v34, v153
	s_nop 1
	v_cndmask_b32_e32 v21, v145, v21, vcc
	v_cmp_le_i32_e32 vcc, v34, v160
	v_or_b32_e32 v34, 10, v33
	s_nop 0
	v_cndmask_b32_e32 v5, v145, v5, vcc
	v_cmp_le_i32_e32 vcc, v34, v153
	s_nop 1
	v_cndmask_b32_e32 v22, v145, v22, vcc
	v_cmp_le_i32_e32 vcc, v34, v160
	v_or_b32_e32 v34, 11, v33
	s_nop 0
	v_cndmask_b32_e32 v6, v145, v6, vcc
	v_cmp_le_i32_e32 vcc, v34, v153
	s_nop 1
	v_cndmask_b32_e32 v23, v145, v23, vcc
	v_cmp_le_i32_e32 vcc, v34, v160
	v_or_b32_e32 v34, 16, v33
	s_nop 0
	v_cndmask_b32_e32 v7, v145, v7, vcc
	v_cmp_le_i32_e32 vcc, v34, v153
	s_nop 1
	v_cndmask_b32_e32 v24, v145, v24, vcc
	v_cmp_le_i32_e32 vcc, v34, v160
	v_or_b32_e32 v34, 17, v33
	s_nop 0
	v_cndmask_b32_e32 v8, v145, v8, vcc
	v_cmp_le_i32_e32 vcc, v34, v153
	s_nop 1
	v_cndmask_b32_e32 v25, v145, v25, vcc
	v_cmp_le_i32_e32 vcc, v34, v160
	v_or_b32_e32 v34, 18, v33
	s_nop 0
	v_cndmask_b32_e32 v9, v145, v9, vcc
	v_cmp_le_i32_e32 vcc, v34, v153
	s_nop 1
	v_cndmask_b32_e32 v26, v145, v26, vcc
	v_cmp_le_i32_e32 vcc, v34, v160
	v_or_b32_e32 v34, 19, v33
	s_nop 0
	v_cndmask_b32_e32 v10, v145, v10, vcc
	v_cmp_le_i32_e32 vcc, v34, v153
	s_nop 1
	v_cndmask_b32_e32 v27, v145, v27, vcc
	v_cmp_le_i32_e32 vcc, v34, v160
	v_or_b32_e32 v34, 24, v33
	s_nop 0
	v_cndmask_b32_e32 v11, v145, v11, vcc
	v_cmp_le_i32_e32 vcc, v34, v153
	s_nop 1
	v_cndmask_b32_e32 v28, v145, v28, vcc
	v_cmp_le_i32_e32 vcc, v34, v160
	v_or_b32_e32 v34, 25, v33
	s_nop 0
	v_cndmask_b32_e32 v12, v145, v12, vcc
	v_cmp_le_i32_e32 vcc, v34, v153
	s_nop 1
	v_cndmask_b32_e32 v29, v145, v29, vcc
	v_cmp_le_i32_e32 vcc, v34, v160
	v_or_b32_e32 v34, 26, v33
	v_or_b32_e32 v33, 27, v33
	v_cndmask_b32_e32 v13, v145, v13, vcc
	v_cmp_le_i32_e32 vcc, v34, v153
	s_nop 1
	v_cndmask_b32_e32 v30, v145, v30, vcc
	v_cmp_le_i32_e32 vcc, v34, v160
	s_nop 1
	v_cndmask_b32_e32 v14, v145, v14, vcc
	v_cmp_le_i32_e32 vcc, v33, v153
	s_nop 1
	v_cndmask_b32_e32 v31, v145, v31, vcc
	v_cmp_le_i32_e32 vcc, v33, v160
	s_nop 1
	v_cndmask_b32_e32 v15, v145, v15, vcc
.LBB0_467:
	s_nop 8
	v_max_f32_e32 v33, v17, v17
	v_max_f32_e32 v34, v16, v16
	v_max_f32_e32 v33, v34, v33
	v_max3_f32 v33, v33, v18, v19
	v_max3_f32 v33, v33, v20, v21
	v_max3_f32 v33, v33, v22, v23
	v_max3_f32 v33, v33, v24, v25
	v_max3_f32 v33, v33, v26, v27
	v_max3_f32 v33, v33, v28, v29
	v_max3_f32 v33, v33, v30, v31
	v_max3_f32 v33, v33, v0, v1
	v_max3_f32 v33, v33, v2, v3
	v_max3_f32 v33, v33, v4, v5
	v_max3_f32 v33, v33, v6, v7
	v_max3_f32 v33, v33, v8, v9
	v_max3_f32 v33, v33, v10, v11
	v_max3_f32 v33, v33, v12, v13
	v_max3_f32 v33, v33, v14, v15
	v_mov_b32_e32 v34, v33
	s_nop 1
	v_permlane32_swap_b32_e32 v33, v34
	v_max_f32_e32 v34, v34, v34
	v_max_f32_e32 v33, v33, v33
	v_max_f32_e32 v33, v33, v34
	s_add_i32 s4, 0, 0x10000
	v_add_f32_e32 v34, 0x7149f2ca, v33
	s_cmp_lg_u32 0, -1
	v_cmp_ge_f32_e32 vcc, s16, v34
	s_cselect_b32 s25, 0, 0
	s_cmp_eq_u64 vcc, exec
	s_cselect_b64 vcc, -1, 0
	s_and_b64 s[30:31], s[64:65], exec
	s_cselect_b32 s5, s24, 64
	v_add_u32_e32 v34, s5, v158
	v_ashrrev_i32_e32 v35, 31, v34
	v_lshlrev_b64 v[42:43], 10, v[34:35]
	v_add_u32_e32 v34, 32, v34
	v_lshlrev_b32_e32 v32, 3, v32
	v_ashrrev_i32_e32 v35, 31, v34
	v_lshlrev_b32_e32 v32, 1, v32
	v_lshlrev_b64 v[46:47], 10, v[34:35]
	v_or_b32_e32 v42, v42, v32
	v_or_b32_e32 v46, v46, v32
	v_lshl_add_u64 v[36:37], s[68:69], 0, v[42:43]
	v_lshl_add_u64 v[38:39], s[68:69], 0, v[46:47]
	v_lshl_add_u64 v[42:43], s[6:7], 0, v[42:43]
	v_lshl_add_u64 v[46:47], s[6:7], 0, v[46:47]
	s_nop 0
	v_and_b32_e32 v161, 63, v148
	v_and_b32_e32 v50, 0x3fffffc0, v148
	v_lshlrev_b32_e32 v51, 4, v161
	v_lshl_add_u32 v152, v50, 2, s4
	v_lshlrev_b32_e32 v50, 3, v161
	v_lshlrev_b32_e32 v52, 1, v161
	v_and_b32_e32 v51, 0xc0, v51
	v_max_f32_e32 v33, 0xf149f2ca, v33
	v_and_b32_e32 v52, 32, v52
	v_and_b32_e32 v53, 0x100, v50
	v_and_or_b32 v50, v50, 24, v51
	v_or3_b32 v154, v50, v52, v53
	v_sub_f32_e32 v50, 0xf149f2ca, v33
	v_cndmask_b32_e32 v177, v33, v146, vcc
	v_exp_f32_e32 v50, v50
	v_sub_f32_e32 v16, v16, v177
	v_sub_f32_e32 v17, v17, v177
	v_sub_f32_e32 v18, v18, v177
	v_sub_f32_e32 v19, v19, v177
	v_sub_f32_e32 v20, v20, v177
	v_sub_f32_e32 v21, v21, v177
	v_sub_f32_e32 v22, v22, v177
	v_sub_f32_e32 v23, v23, v177
	v_sub_f32_e32 v24, v24, v177
	v_sub_f32_e32 v25, v25, v177
	v_sub_f32_e32 v26, v26, v177
	v_sub_f32_e32 v27, v27, v177
	v_sub_f32_e32 v28, v28, v177
	v_sub_f32_e32 v29, v29, v177
	v_sub_f32_e32 v30, v30, v177
	v_sub_f32_e32 v31, v31, v177
	v_exp_f32_e32 v196, v16
	v_exp_f32_e32 v198, v17
	v_exp_f32_e32 v194, v18
	v_exp_f32_e32 v197, v19
	v_exp_f32_e32 v192, v20
	v_exp_f32_e32 v195, v21
	v_exp_f32_e32 v191, v22
	v_exp_f32_e32 v193, v23
	v_exp_f32_e32 v188, v24
	v_exp_f32_e32 v190, v25
	v_exp_f32_e32 v186, v26
	v_exp_f32_e32 v189, v27
	v_exp_f32_e32 v184, v28
	v_exp_f32_e32 v187, v29
	v_exp_f32_e32 v183, v30
	v_exp_f32_e32 v185, v31
	s_waitcnt vmcnt(0)
	s_cmp_lg_u32 s14, 0
	v_mov_b32_e32 v136, v130
	v_mov_b32_e32 v137, v130
	v_mov_b32_e32 v134, v130
	v_mov_b32_e32 v135, v130
	v_sub_f32_e32 v65, v15, v177
	v_sub_f32_e32 v64, v14, v177
	v_sub_f32_e32 v67, v13, v177
	v_sub_f32_e32 v66, v12, v177
	v_sub_f32_e32 v69, v11, v177
	v_sub_f32_e32 v68, v10, v177
	v_sub_f32_e32 v71, v9, v177
	v_sub_f32_e32 v70, v8, v177
	v_sub_f32_e32 v73, v7, v177
	v_sub_f32_e32 v72, v6, v177
	v_sub_f32_e32 v75, v5, v177
	v_sub_f32_e32 v74, v4, v177
	v_sub_f32_e32 v77, v3, v177
	v_sub_f32_e32 v76, v2, v177
	v_sub_f32_e32 v79, v1, v177
	v_sub_f32_e32 v78, v0, v177
	v_cndmask_b32_e64 v156, v50, 1.0, vcc
	s_cselect_b64 s[66:67], -1, 0
	s_cmp_eq_u32 s14, 0
	v_cmp_gt_u32_e64 s[4:5], 32, v161
	v_add_u32_e32 v176, s25, v154
	v_lshl_add_u32 v173, v155, 2, v152
	s_waitcnt vmcnt(3)
	ds_write_b128 v174, v[236:239] offset:16384
	s_waitcnt vmcnt(2)
	ds_write_b128 v175, v[240:243] offset:16384
	s_waitcnt vmcnt(1)
	ds_write_b128 v171, v[244:247] offset:49152
	s_waitcnt vmcnt(0)
	ds_write_b128 v172, v[226:229] offset:49152
	s_waitcnt lgkmcnt(0)
	s_barrier
	s_cbranch_scc1 .LBB0_484
	v_mov_b32_e32 v33, v128
	s_cmp_lg_u32 0, -1
	v_lshl_add_u64 v[138:139], s[6:7], 0, v[32:33]
	s_cselect_b32 s6, 0, 0
	s_addk_i32 s6, 0x4000
	v_mov_b32_e32 v157, 0
	v_lshl_add_u64 v[132:133], s[68:69], 0, v[32:33]
	v_sub_u32_e32 v178, v155, v159
	v_lshl_add_u32 v179, v151, 2, v152
	v_add_u32_e32 v180, s6, v154
	s_add_i32 s29, s27, -4
	s_mov_b32 s30, 3
	v_mov_b32_e32 v48, 0
	v_mov_b32_e32 v49, v157
	v_mov_b32_e32 v50, v157
	v_mov_b32_e32 v51, v157
	v_mov_b32_e32 v52, v157
	v_mov_b32_e32 v53, v157
	v_mov_b32_e32 v54, v157
	v_mov_b32_e32 v55, v157
	v_mov_b32_e32 v56, v157
	v_mov_b32_e32 v57, v157
	v_mov_b32_e32 v58, v157
	v_mov_b32_e32 v59, v157
	v_mov_b32_e32 v60, v157
	v_mov_b32_e32 v61, v157
	v_mov_b32_e32 v62, v157
	v_mov_b32_e32 v63, v157
	v_mov_b32_e32 v32, 0
	v_mov_b32_e32 v33, v157
	v_mov_b32_e32 v34, v157
	v_mov_b32_e32 v35, v157
	v_mov_b32_e32 v36, v157
	v_mov_b32_e32 v37, v157
	v_mov_b32_e32 v38, v157
	v_mov_b32_e32 v39, v157
	v_mov_b32_e32 v40, v157
	v_mov_b32_e32 v41, v157
	v_mov_b32_e32 v42, v157
	v_mov_b32_e32 v43, v157
	v_mov_b32_e32 v44, v157
	v_mov_b32_e32 v45, v157
	v_mov_b32_e32 v46, v157
	v_mov_b32_e32 v47, v157
	v_mov_b32_e32 v16, 0
	v_mov_b32_e32 v17, v157
	v_mov_b32_e32 v18, v157
	v_mov_b32_e32 v19, v157
	v_mov_b32_e32 v20, v157
	v_mov_b32_e32 v21, v157
	v_mov_b32_e32 v22, v157
	v_mov_b32_e32 v23, v157
	v_mov_b32_e32 v24, v157
	v_mov_b32_e32 v25, v157
	v_mov_b32_e32 v26, v157
	v_mov_b32_e32 v27, v157
	v_mov_b32_e32 v28, v157
	v_mov_b32_e32 v29, v157
	v_mov_b32_e32 v30, v157
	v_mov_b32_e32 v31, v157
	v_mov_b32_e32 v0, 0
	v_mov_b32_e32 v1, v157
	v_mov_b32_e32 v2, v157
	v_mov_b32_e32 v3, v157
	v_mov_b32_e32 v4, v157
	v_mov_b32_e32 v5, v157
	v_mov_b32_e32 v6, v157
	v_mov_b32_e32 v7, v157
	v_mov_b32_e32 v8, v157
	v_mov_b32_e32 v9, v157
	v_mov_b32_e32 v10, v157
	v_mov_b32_e32 v11, v157
	v_mov_b32_e32 v12, v157
	v_mov_b32_e32 v13, v157
	v_mov_b32_e32 v14, v157
	v_mov_b32_e32 v15, v157
